# retA state update: the 18 v_pk_mul_f32 (S *= decay) between the MFMAs split into scalar v_mul_f32 pairs (asm guide 7.5)
# baseline (speedup 1.0000x reference)
.LBB0_340:
	v_cvt_pk_bf16_f32 v104, v104, v105
	v_cvt_pk_bf16_f32 v105, v106, v107
	s_nop 2
	v_add_u32_e32 v106, s22, v134
	ds_write_b64 v106, v[104:105]
	ds_read_b64 v[104:105], v131
	ds_read_b64 v[106:107], v131 offset:32
	v_add_u32_e32 v139, 0x2000, v131
	v_add_u32_e32 v141, 0x4000, v131
	v_add_u32_e32 v143, 0x6000, v131
	ds_read_b64 v[108:109], v139 offset:256
	ds_read_b64 v[110:111], v139 offset:288
	ds_read_b64 v[112:113], v141 offset:512
	ds_read_b64 v[114:115], v141 offset:544
	v_cvt_pk_bf16_f32 v116, v100, v101
	v_cvt_pk_bf16_f32 v117, v102, v103
	v_cvt_pk_bf16_f32 v118, v88, v89
	v_cvt_pk_bf16_f32 v119, v90, v91
	ds_read_b64 v[120:121], v143 offset:768
	ds_read_b64 v[122:123], v143 offset:800
	s_lshl_b32 s13, s41, 6
	s_and_b64 s[16:17], s[16:17], exec
	s_cselect_b32 s12, s33, s1
	s_add_i32 s13, s13, s12
	s_waitcnt lgkmcnt(6)
	v_mfma_f32_16x16x32_bf16 v[104:107], v[116:119], v[104:107], 0
	ds_read_b64 v[124:125], v131 offset:64
	ds_read_b64 v[126:127], v131 offset:96
	s_waitcnt lgkmcnt(6)
	v_mfma_f32_16x16x32_bf16 v[108:111], v[116:119], v[108:111], 0
	ds_read_b64 v[148:149], v139 offset:320
	ds_read_b64 v[150:151], v139 offset:352
	s_waitcnt lgkmcnt(6)
	v_mfma_f32_16x16x32_bf16 v[112:115], v[116:119], v[112:115], 0
	global_load_dwordx4 v[4:7], v[12:13], off
	ds_read_b64 v[152:153], v141 offset:576
	ds_read_b64 v[154:155], v141 offset:608
	s_waitcnt lgkmcnt(6)
	v_mfma_f32_16x16x32_bf16 v[116:119], v[116:119], v[120:123], 0
	v_cvt_pk_bf16_f32 v120, v84, v85
	v_cvt_pk_bf16_f32 v121, v86, v87
	v_cvt_pk_bf16_f32 v122, v80, v81
	v_cvt_pk_bf16_f32 v123, v82, v83
	ds_read_b64 v[156:157], v143 offset:832
	ds_read_b64 v[158:159], v143 offset:864
	s_waitcnt lgkmcnt(6)
	v_mfma_f32_16x16x32_bf16 v[104:107], v[120:123], v[124:127], v[104:107]
	ds_read_b64 v[124:125], v131 offset:128
	ds_read_b64 v[126:127], v131 offset:160
	s_waitcnt lgkmcnt(6)
	v_mfma_f32_16x16x32_bf16 v[108:111], v[120:123], v[148:151], v[108:111]
	global_load_dwordx4 v[8:11], v[12:13], off offset:128
	ds_read_b64 v[148:149], v139 offset:384
	ds_read_b64 v[150:151], v139 offset:416
	s_waitcnt lgkmcnt(6)
	v_mfma_f32_16x16x32_bf16 v[112:115], v[120:123], v[152:155], v[112:115]
	ds_read_b64 v[152:153], v141 offset:640
	ds_read_b64 v[154:155], v141 offset:672
	s_waitcnt lgkmcnt(6)
	v_mfma_f32_16x16x32_bf16 v[116:119], v[120:123], v[156:159], v[116:119]
	v_cvt_pk_bf16_f32 v120, v76, v77
	v_cvt_pk_bf16_f32 v121, v78, v79
	v_cvt_pk_bf16_f32 v122, v72, v73
	v_cvt_pk_bf16_f32 v123, v74, v75
	ds_read_b64 v[156:157], v143 offset:896
	ds_read_b64 v[158:159], v143 offset:928
	s_waitcnt lgkmcnt(6)
	v_mfma_f32_16x16x32_bf16 v[104:107], v[120:123], v[124:127], v[104:107]
	global_load_dwordx4 v[12:15], v[16:17], off
	ds_read_b64 v[124:125], v131 offset:192
	ds_read_b64 v[126:127], v131 offset:224
	s_waitcnt lgkmcnt(6)
	v_mfma_f32_16x16x32_bf16 v[108:111], v[120:123], v[148:151], v[108:111]
	ds_read_b64 v[148:149], v139 offset:448
	ds_read_b64 v[150:151], v139 offset:480
	s_waitcnt lgkmcnt(6)
	v_mfma_f32_16x16x32_bf16 v[112:115], v[120:123], v[152:155], v[112:115]
	ds_read_b64 v[152:153], v141 offset:704
	ds_read_b64 v[154:155], v141 offset:736
	s_waitcnt lgkmcnt(6)
	v_mfma_f32_16x16x32_bf16 v[116:119], v[120:123], v[156:159], v[116:119]
	global_load_dwordx4 v[16:19], v[16:17], off offset:128
	v_cvt_pk_bf16_f32 v120, v68, v69
	v_cvt_pk_bf16_f32 v121, v70, v71
	v_cvt_pk_bf16_f32 v122, v64, v65
	v_cvt_pk_bf16_f32 v123, v66, v67
	ds_read_b64 v[156:157], v143 offset:960
	ds_read_b64 v[158:159], v143 offset:992
	s_waitcnt lgkmcnt(6)
	v_mfma_f32_16x16x32_bf16 v[104:107], v[120:123], v[124:127], v[104:107]
	ds_read_b64 v[124:125], v131 offset:256
	ds_read_b64 v[126:127], v131 offset:288
	s_waitcnt lgkmcnt(6)
	v_mfma_f32_16x16x32_bf16 v[108:111], v[120:123], v[148:151], v[108:111]
	ds_read_b64 v[148:149], v139 offset:512
	ds_read_b64 v[150:151], v139 offset:544
	s_waitcnt lgkmcnt(6)
	v_mfma_f32_16x16x32_bf16 v[112:115], v[120:123], v[152:155], v[112:115]
	global_load_dwordx4 v[20:23], v[22:23], off
	ds_read_b64 v[152:153], v141 offset:768
	ds_read_b64 v[154:155], v141 offset:800
	s_waitcnt lgkmcnt(6)
	v_mfma_f32_16x16x32_bf16 v[116:119], v[120:123], v[156:159], v[116:119]
	v_cvt_pk_bf16_f32 v120, v60, v61
	v_cvt_pk_bf16_f32 v121, v62, v63
	v_cvt_pk_bf16_f32 v122, v56, v57
	v_cvt_pk_bf16_f32 v123, v58, v59
	ds_read_b64 v[156:157], v143 offset:1024
	ds_read_b64 v[158:159], v143 offset:1056
	s_waitcnt lgkmcnt(6)
	v_mfma_f32_16x16x32_bf16 v[104:107], v[120:123], v[124:127], v[104:107]
	ds_read_b64 v[124:125], v131 offset:320
	ds_read_b64 v[126:127], v131 offset:352
	s_waitcnt lgkmcnt(6)
	v_mfma_f32_16x16x32_bf16 v[108:111], v[120:123], v[148:151], v[108:111]
	global_load_dwordx4 v[24:27], v[28:29], off
	ds_read_b64 v[148:149], v139 offset:576
	ds_read_b64 v[150:151], v139 offset:608
	s_waitcnt lgkmcnt(6)
	v_mfma_f32_16x16x32_bf16 v[112:115], v[120:123], v[152:155], v[112:115]
	ds_read_b64 v[152:153], v141 offset:832
	ds_read_b64 v[154:155], v141 offset:864
	s_waitcnt lgkmcnt(6)
	v_mfma_f32_16x16x32_bf16 v[116:119], v[120:123], v[156:159], v[116:119]
	v_cvt_pk_bf16_f32 v120, v52, v53
	v_cvt_pk_bf16_f32 v121, v54, v55
	v_cvt_pk_bf16_f32 v122, v48, v49
	v_cvt_pk_bf16_f32 v123, v50, v51
	ds_read_b64 v[156:157], v143 offset:1088
	ds_read_b64 v[158:159], v143 offset:1120
	s_waitcnt lgkmcnt(6)
	v_mfma_f32_16x16x32_bf16 v[104:107], v[120:123], v[124:127], v[104:107]
	global_load_dwordx4 v[28:31], v[28:29], off offset:128
	ds_read_b64 v[124:125], v131 offset:384
	ds_read_b64 v[126:127], v131 offset:416
	s_waitcnt lgkmcnt(6)
	v_mfma_f32_16x16x32_bf16 v[108:111], v[120:123], v[148:151], v[108:111]
	ds_read_b64 v[148:149], v139 offset:640
	ds_read_b64 v[150:151], v139 offset:672
	s_waitcnt lgkmcnt(6)
	v_mfma_f32_16x16x32_bf16 v[112:115], v[120:123], v[152:155], v[112:115]
	ds_read_b64 v[152:153], v141 offset:896
	ds_read_b64 v[154:155], v141 offset:928
	s_waitcnt lgkmcnt(6)
	v_mfma_f32_16x16x32_bf16 v[116:119], v[120:123], v[156:159], v[116:119]
	global_load_dwordx4 v[32:35], v[38:39], off
	v_cvt_pk_bf16_f32 v120, v44, v45
	v_cvt_pk_bf16_f32 v121, v46, v47
	v_cvt_pk_bf16_f32 v122, v0, v1
	v_cvt_pk_bf16_f32 v123, v2, v3
	ds_read_b64 v[156:157], v143 offset:1152
	ds_read_b64 v[158:159], v143 offset:1184
	s_waitcnt lgkmcnt(6)
	v_mfma_f32_16x16x32_bf16 v[104:107], v[120:123], v[124:127], v[104:107]
	ds_read_b64 v[124:125], v131 offset:448
	ds_read_b64 v[126:127], v131 offset:480
	s_waitcnt lgkmcnt(6)
	v_mfma_f32_16x16x32_bf16 v[108:111], v[120:123], v[148:151], v[108:111]
	ds_read_b64 v[148:149], v139 offset:704
	ds_read_b64 v[150:151], v139 offset:736
	s_waitcnt lgkmcnt(6)
	v_mfma_f32_16x16x32_bf16 v[112:115], v[120:123], v[152:155], v[112:115]
	global_load_dwordx4 v[36:39], v[38:39], off offset:128
	ds_read_b64 v[152:153], v141 offset:960
	ds_read_b64 v[154:155], v141 offset:992
	s_waitcnt lgkmcnt(6)
	v_mfma_f32_16x16x32_bf16 v[156:159], v[120:123], v[156:159], v[116:119]
	v_cvt_pk_bf16_f32 v180, v92, v93
	v_cvt_pk_bf16_f32 v181, v94, v95
	v_cvt_pk_bf16_f32 v182, v96, v97
	v_cvt_pk_bf16_f32 v183, v98, v99
	ds_read_b64 v[190:191], v143 offset:1216
	ds_read_b64 v[192:193], v143 offset:1248
	s_waitcnt lgkmcnt(6)
	v_mfma_f32_16x16x32_bf16 v[124:127], v[180:183], v[124:127], v[104:107]
	s_waitcnt lgkmcnt(4)
	v_mfma_f32_16x16x32_bf16 v[120:123], v[180:183], v[148:151], v[108:111]
	global_load_dwordx4 v[40:43], v[40:41], off
	s_waitcnt lgkmcnt(2)
	v_mfma_f32_16x16x32_bf16 v[116:119], v[180:183], v[152:155], v[112:115]
	s_waitcnt lgkmcnt(0)
	v_mfma_f32_16x16x32_bf16 v[108:111], v[180:183], v[190:193], v[156:159]
	ds_read_b64_tr_b16 v[150:151], v135 offset:42496
	ds_read_b64_tr_b16 v[148:149], v135 offset:33792
	ds_read_b64_tr_b16 v[112:113], v185
	ds_read_b64_tr_b16 v[114:115], v185 offset:4608
	ds_read_b64_tr_b16 v[104:105], v185 offset:9216
	ds_read_b64_tr_b16 v[106:107], v185 offset:13824
	ds_read_b64_tr_b16 v[154:155], v135 offset:42528
	ds_read_b64_tr_b16 v[152:153], v135 offset:33824
	ds_read_b64_tr_b16 v[156:157], v135 offset:51200
	ds_read_b64_tr_b16 v[158:159], v135 offset:59904
	ds_read_b64_tr_b16 v[182:183], v135 offset:59936
	ds_read_b64_tr_b16 v[180:181], v135 offset:51232
	s_waitcnt lgkmcnt(8)
	v_mfma_f32_16x16x32_bf16 v[100:103], v[148:151], v[112:115], v[100:103]
	ds_read_b64_tr_b16 v[148:149], v135 offset:33856
	ds_read_b64_tr_b16 v[150:151], v135 offset:42560
	s_waitcnt lgkmcnt(4)
	v_mfma_f32_16x16x32_bf16 v[100:103], v[156:159], v[104:107], v[100:103]
	ds_read_b64_tr_b16 v[156:157], v135 offset:51264
	ds_read_b64_tr_b16 v[158:159], v135 offset:59968
	v_mfma_f32_16x16x32_bf16 v[88:91], v[152:155], v[112:115], v[88:91]
	v_mov_b32_e32 v143, v142
	s_nop 3
	v_mul_f32_e32 v102, v142, v102
	v_mul_f32_e32 v103, v143, v103
	v_mul_f32_e32 v100, v144, v100
	v_mul_f32_e32 v101, v145, v101
	ds_read_b64_tr_b16 v[152:153], v135 offset:33888
	ds_read_b64_tr_b16 v[154:155], v135 offset:42592
	s_waitcnt lgkmcnt(6)
	v_mfma_f32_16x16x32_bf16 v[88:91], v[180:183], v[104:107], v[88:91]
	ds_read_b64_tr_b16 v[180:181], v135 offset:51296
	ds_read_b64_tr_b16 v[182:183], v135 offset:60000
	s_waitcnt lgkmcnt(6)
	v_mfma_f32_16x16x32_bf16 v[84:87], v[148:151], v[112:115], v[84:87]
	s_nop 3
	v_mul_f32_e64 v90, v142, v90
	v_mul_f32_e64 v91, v143, v91
	v_mul_f32_e32 v88, v144, v88
	v_mul_f32_e32 v89, v145, v89
	ds_read_b64_tr_b16 v[148:149], v135 offset:33920
	ds_read_b64_tr_b16 v[150:151], v135 offset:42624
	s_waitcnt lgkmcnt(6)
	v_mfma_f32_16x16x32_bf16 v[84:87], v[156:159], v[104:107], v[84:87]
	ds_read_b64_tr_b16 v[156:157], v135 offset:51328
	ds_read_b64_tr_b16 v[158:159], v135 offset:60032
	s_waitcnt lgkmcnt(6)
	v_mfma_f32_16x16x32_bf16 v[80:83], v[152:155], v[112:115], v[80:83]
	s_nop 3
	v_mul_f32_e64 v86, v142, v86
	v_mul_f32_e64 v87, v143, v87
	v_mul_f32_e32 v84, v144, v84
	v_mul_f32_e32 v85, v145, v85
	ds_read_b64_tr_b16 v[152:153], v135 offset:33952
	ds_read_b64_tr_b16 v[154:155], v135 offset:42656
	s_waitcnt lgkmcnt(6)
	v_mfma_f32_16x16x32_bf16 v[80:83], v[180:183], v[104:107], v[80:83]
	ds_read_b64_tr_b16 v[180:181], v135 offset:51360
	ds_read_b64_tr_b16 v[182:183], v135 offset:60064
	s_waitcnt lgkmcnt(6)
	v_mfma_f32_16x16x32_bf16 v[76:79], v[148:151], v[112:115], v[76:79]
	s_nop 3
	v_mul_f32_e64 v82, v142, v82
	v_mul_f32_e64 v83, v143, v83
	v_mul_f32_e32 v80, v144, v80
	v_mul_f32_e32 v81, v145, v81
	ds_read_b64_tr_b16 v[148:149], v135 offset:33984
	ds_read_b64_tr_b16 v[150:151], v135 offset:42688
	s_waitcnt lgkmcnt(6)
	v_mfma_f32_16x16x32_bf16 v[76:79], v[156:159], v[104:107], v[76:79]
	ds_read_b64_tr_b16 v[156:157], v135 offset:51392
	ds_read_b64_tr_b16 v[158:159], v135 offset:60096
	s_waitcnt lgkmcnt(6)
	v_mfma_f32_16x16x32_bf16 v[72:75], v[152:155], v[112:115], v[72:75]
	s_nop 3
	v_mul_f32_e64 v78, v142, v78
	v_mul_f32_e64 v79, v143, v79
	v_mul_f32_e32 v76, v144, v76
	v_mul_f32_e32 v77, v145, v77
	ds_read_b64_tr_b16 v[152:153], v135 offset:34016
	ds_read_b64_tr_b16 v[154:155], v135 offset:42720
	s_waitcnt lgkmcnt(6)
	v_mfma_f32_16x16x32_bf16 v[72:75], v[180:183], v[104:107], v[72:75]
	ds_read_b64_tr_b16 v[180:181], v135 offset:51424
	ds_read_b64_tr_b16 v[182:183], v135 offset:60128
	s_waitcnt lgkmcnt(6)
	v_mfma_f32_16x16x32_bf16 v[68:71], v[148:151], v[112:115], v[68:71]
	s_nop 3
	v_mul_f32_e64 v74, v142, v74
	v_mul_f32_e64 v75, v143, v75
	v_mul_f32_e32 v72, v144, v72
	v_mul_f32_e32 v73, v145, v73
	ds_read_b64_tr_b16 v[148:149], v135 offset:34048
	ds_read_b64_tr_b16 v[150:151], v135 offset:42752
	s_waitcnt lgkmcnt(6)
	v_mfma_f32_16x16x32_bf16 v[68:71], v[156:159], v[104:107], v[68:71]
	ds_read_b64_tr_b16 v[156:157], v135 offset:51456
	ds_read_b64_tr_b16 v[158:159], v135 offset:60160
	s_waitcnt lgkmcnt(6)
	v_mfma_f32_16x16x32_bf16 v[64:67], v[152:155], v[112:115], v[64:67]
	s_nop 3
	v_mul_f32_e64 v70, v142, v70
	v_mul_f32_e64 v71, v143, v71
	v_mul_f32_e32 v68, v144, v68
	v_mul_f32_e32 v69, v145, v69
	ds_read_b64_tr_b16 v[152:153], v135 offset:34080
	ds_read_b64_tr_b16 v[154:155], v135 offset:42784
	s_waitcnt lgkmcnt(6)
	v_mfma_f32_16x16x32_bf16 v[64:67], v[180:183], v[104:107], v[64:67]
	ds_read_b64_tr_b16 v[180:181], v135 offset:51488
	ds_read_b64_tr_b16 v[182:183], v135 offset:60192
	s_waitcnt lgkmcnt(6)
	v_mfma_f32_16x16x32_bf16 v[60:63], v[148:151], v[112:115], v[60:63]
	s_nop 3
	v_mul_f32_e64 v66, v142, v66
	v_mul_f32_e64 v67, v143, v67
	v_mul_f32_e32 v64, v144, v64
	v_mul_f32_e32 v65, v145, v65
	ds_read_b64_tr_b16 v[148:149], v135 offset:34112
	ds_read_b64_tr_b16 v[150:151], v135 offset:42816
	s_waitcnt lgkmcnt(6)
	v_mfma_f32_16x16x32_bf16 v[60:63], v[156:159], v[104:107], v[60:63]
	ds_read_b64_tr_b16 v[156:157], v135 offset:51520
	ds_read_b64_tr_b16 v[158:159], v135 offset:60224
	s_waitcnt lgkmcnt(6)
	v_mfma_f32_16x16x32_bf16 v[56:59], v[152:155], v[112:115], v[56:59]
	s_nop 3
	v_mul_f32_e64 v62, v142, v62
	v_mul_f32_e64 v63, v143, v63
	v_mul_f32_e32 v60, v144, v60
	v_mul_f32_e32 v61, v145, v61
	ds_read_b64_tr_b16 v[152:153], v135 offset:34144
	ds_read_b64_tr_b16 v[154:155], v135 offset:42848
	s_waitcnt lgkmcnt(6)
	v_mfma_f32_16x16x32_bf16 v[56:59], v[180:183], v[104:107], v[56:59]
	ds_read_b64_tr_b16 v[180:181], v135 offset:51552
	ds_read_b64_tr_b16 v[182:183], v135 offset:60256
	s_waitcnt lgkmcnt(6)
	v_mfma_f32_16x16x32_bf16 v[52:55], v[148:151], v[112:115], v[52:55]
	s_nop 3
	v_mul_f32_e64 v58, v142, v58
	v_mul_f32_e64 v59, v143, v59
	v_mul_f32_e32 v56, v144, v56
	v_mul_f32_e32 v57, v145, v57
	ds_read_b64_tr_b16 v[148:149], v135 offset:34176
	ds_read_b64_tr_b16 v[150:151], v135 offset:42880
	s_waitcnt lgkmcnt(6)
	v_mfma_f32_16x16x32_bf16 v[52:55], v[156:159], v[104:107], v[52:55]
	ds_read_b64_tr_b16 v[156:157], v135 offset:51584
	ds_read_b64_tr_b16 v[158:159], v135 offset:60288
	s_waitcnt lgkmcnt(6)
	v_mfma_f32_16x16x32_bf16 v[48:51], v[152:155], v[112:115], v[48:51]
	s_nop 3
	v_mul_f32_e64 v54, v142, v54
	v_mul_f32_e64 v55, v143, v55
	v_mul_f32_e32 v52, v144, v52
	v_mul_f32_e32 v53, v145, v53
	ds_read_b64_tr_b16 v[152:153], v135 offset:34208
	ds_read_b64_tr_b16 v[154:155], v135 offset:42912
	s_waitcnt lgkmcnt(6)
	v_mfma_f32_16x16x32_bf16 v[48:51], v[180:183], v[104:107], v[48:51]
	ds_read_b64_tr_b16 v[180:181], v135 offset:51616
	ds_read_b64_tr_b16 v[182:183], v135 offset:60320
	s_waitcnt lgkmcnt(6)
	v_mfma_f32_16x16x32_bf16 v[44:47], v[148:151], v[112:115], v[44:47]
	s_nop 3
	v_mul_f32_e64 v50, v142, v50
	v_mul_f32_e64 v51, v143, v51
	v_mul_f32_e32 v48, v144, v48
	v_mul_f32_e32 v49, v145, v49
	ds_read_b64_tr_b16 v[148:149], v135 offset:34240
	ds_read_b64_tr_b16 v[150:151], v135 offset:42944
	s_waitcnt lgkmcnt(6)
	v_mfma_f32_16x16x32_bf16 v[44:47], v[156:159], v[104:107], v[44:47]
	ds_read_b64_tr_b16 v[156:157], v135 offset:51648
	ds_read_b64_tr_b16 v[158:159], v135 offset:60352
	s_waitcnt lgkmcnt(6)
	v_mfma_f32_16x16x32_bf16 v[0:3], v[152:155], v[112:115], v[0:3]
	s_nop 3
	v_mul_f32_e64 v46, v142, v46
	v_mul_f32_e64 v47, v143, v47
	v_mul_f32_e32 v44, v144, v44
	v_mul_f32_e32 v45, v145, v45
	ds_read_b64_tr_b16 v[152:153], v135 offset:34272
	ds_read_b64_tr_b16 v[154:155], v135 offset:42976
	s_waitcnt lgkmcnt(6)
	v_mfma_f32_16x16x32_bf16 v[0:3], v[180:183], v[104:107], v[0:3]
	ds_read_b64_tr_b16 v[180:181], v135 offset:51680
	ds_read_b64_tr_b16 v[182:183], v135 offset:60384
	s_waitcnt lgkmcnt(6)
	v_mfma_f32_16x16x32_bf16 v[92:95], v[148:151], v[112:115], v[92:95]
	s_nop 3
	v_mul_f32_e64 v2, v142, v2
	v_mul_f32_e64 v3, v143, v3
	v_mul_f32_e32 v0, v144, v0
	v_mul_f32_e32 v1, v145, v1
	s_waitcnt lgkmcnt(4)
	v_mfma_f32_16x16x32_bf16 v[92:95], v[156:159], v[104:107], v[92:95]
	s_waitcnt lgkmcnt(2)
	v_mfma_f32_16x16x32_bf16 v[96:99], v[152:155], v[112:115], v[96:99]
	s_nop 5
	v_mul_f32_e64 v94, v142, v94
	v_mul_f32_e64 v95, v143, v95
	v_mul_f32_e32 v92, v144, v92
	v_mul_f32_e32 v93, v145, v93
	s_waitcnt lgkmcnt(0)
	v_mfma_f32_16x16x32_bf16 v[96:99], v[180:183], v[104:107], v[96:99]
	s_barrier
	ds_read_b64 v[148:149], v186
	ds_read_b64 v[150:151], v186 offset:32
	ds_read_b64 v[152:153], v186 offset:64
	ds_read_b64 v[154:155], v186 offset:96
	v_add_u32_e32 v139, 0x800, v186
	ds_read_b64 v[156:157], v139 offset:256
	ds_read_b64 v[158:159], v139 offset:288
	ds_read_b64 v[180:181], v139 offset:320
	ds_read_b64 v[182:183], v139 offset:352
	v_add_u32_e32 v139, 0x1000, v186
	ds_read_b64 v[190:191], v139 offset:512
	ds_read_b64 v[192:193], v139 offset:544
	s_ashr_i32 s12, s13, 31
	s_add_u32 s16, s13, s19
	s_addc_u32 s17, s12, 0
	s_lshl_b64 s[16:17], s[16:17], 13
	s_mov_b32 s12, 0x20000
	s_add_i32 s40, s40, 1
	v_mul_f32_e32 v98, v142, v98
	v_mul_f32_e32 v99, v143, v99
	v_mul_f32_e32 v96, v144, v96
	v_mul_f32_e32 v97, v145, v97
	s_cmp_eq_u32 s40, 32
	s_waitcnt lgkmcnt(8)
	v_mfma_f32_16x16x32_bf16 v[124:127], v[112:115], v[148:151], v[124:127]
	ds_read_b64 v[148:149], v139 offset:576
	ds_read_b64 v[150:151], v139 offset:608
	s_waitcnt lgkmcnt(8)
	v_mfma_f32_16x16x32_bf16 v[124:127], v[104:107], v[152:155], v[124:127]
	v_add_u32_e32 v139, 0x1800, v186
	ds_read_b64 v[152:153], v139 offset:768
	ds_read_b64 v[154:155], v139 offset:800
	s_waitcnt lgkmcnt(8)
	v_mfma_f32_16x16x32_bf16 v[120:123], v[112:115], v[156:159], v[120:123]
	ds_read_b64 v[156:157], v139 offset:832
	ds_read_b64 v[158:159], v139 offset:864
	s_waitcnt lgkmcnt(8)
	v_mfma_f32_16x16x32_bf16 v[120:123], v[104:107], v[180:183], v[120:123]
	s_waitcnt lgkmcnt(6)
	v_mfma_f32_16x16x32_bf16 v[116:119], v[112:115], v[190:193], v[116:119]
	s_waitcnt lgkmcnt(4)
	v_mfma_f32_16x16x32_bf16 v[116:119], v[104:107], v[148:151], v[116:119]
	s_waitcnt lgkmcnt(2)
	v_mfma_f32_16x16x32_bf16 v[108:111], v[112:115], v[152:155], v[108:111]
	s_waitcnt lgkmcnt(0)
	v_mfma_f32_16x16x32_bf16 v[104:107], v[104:107], v[156:159], v[108:111]
	s_nop 2
	v_cvt_pk_bf16_f32 v110, v124, v125
	v_cvt_pk_bf16_f32 v111, v126, v127
	v_lshl_add_u64 v[108:109], v[146:147], 0, s[16:17]
	global_store_dwordx2 v[108:109], v[110:111], off
	v_add_co_u32_e32 v112, vcc, 0x20000, v108
	v_cvt_pk_bf16_f32 v114, v120, v121
	v_cvt_pk_bf16_f32 v115, v122, v123
	v_addc_co_u32_e32 v113, vcc, 0, v109, vcc
	global_store_dwordx2 v[112:113], v[114:115], off
	v_add_co_u32_e32 v124, vcc, 0x40000, v108
	v_cvt_pk_bf16_f32 v126, v116, v117
	v_cvt_pk_bf16_f32 v127, v118, v119
	v_addc_co_u32_e32 v125, vcc, 0, v109, vcc
	global_store_dwordx2 v[124:125], v[126:127], off
	v_add_co_u32_e32 v120, vcc, 0x60000, v108
	v_cvt_pk_bf16_f32 v122, v104, v105
	v_cvt_pk_bf16_f32 v123, v106, v107
	v_addc_co_u32_e32 v121, vcc, 0, v109, vcc
	global_store_dwordx2 v[120:121], v[122:123], off
	s_cbranch_scc1 .LBB0_334
